# MLA phase: one static priority raise for waves 4-7 (the two waves of a SIMD run the same program in lockstep)
# baseline (speedup 1.0000x reference)
; #define LAS __attribute__((address_space(3)))
; #define PHASE() size_t z_ = 0; asm volatile("" : "+s"(z_)); unsigned char* ws = args.ws + z_; float* H = args.out + z_; (void)H; (void)ws;
; #define RELANE() int tid = threadIdx.x; asm volatile("" : "+v"(tid)); const int lane = tid & 63; (void)lane;
; __device__ __forceinline__ void mla_unit(LAS unsigned char* lds, int bh, int x, const bf16* QM, const bf16* KM, const bf16* VMT, bf16* OUT, ssq_t* SSo, int tid, int lane, int wave) {
;     const int r32 = lane & 31, hi = lane >> 5, g = wave >> 2, wq = wave & 3;
;     const int q0 = 128 * x, qg = q0 + 32 * wq + r32, T = 2 * (x + 1);
;     LAS bf16* L = (LAS bf16*)lds;
;     LAS bf16* Qs = L + MLA_QOFF;
;     const LAS bf16* Qw = Qs + (32 * wq + r32) * 200 + 8 * hi;
;     const LAS bf16* Kw = L + MLA_KOFF + g * MLA_KS + r32 * 200 + 8 * hi;
;     const LAS bf16* Vw = L + MLA_VOFF + g * MLA_VS + r32 * 36 + 4 * hi;
;     f32x16 o[4];
; #pragma unroll
;     for (int k = 0; k < 4; ++k)
; #pragma unroll
;         for (int r = 0; r < 16; ++r) o[k][r] = 0.f;
;     float mref = 0.f, lrun = 0.f;
;     const bf16* Kb = KM + (size_t)bh * S * 192;
;     const bf16* Vb = VMT + (size_t)bh * 128 * S;
;     u32x4 rk0[3], rv0[2], rk1[3], rv1[2];
;     const unsigned kgo = (unsigned)tid * 16u;
;     const unsigned vgo = (unsigned)((tid >> 3) * S + (tid & 7) * 8) * 2u;
;     unsigned kds[3];
; #pragma unroll
;     for (int i = 0; i < 3; ++i) { const int c = tid + 512 * i, row = c / 24, ch = c - 24 * row; kds[i] = (unsigned)(MLA_KOFF + (row >> 5) * MLA_KS + (row & 31) * 200 + ch * 8); }
;     const unsigned vds = (unsigned)(MLA_VOFF + ((tid & 7) >> 2) * MLA_VS + (tid >> 3) * 36 + (tid & 3) * 8);
; __global__ void __launch_bounds__(512, 2) hybrid_fwd(Args args) {
;     ...
;         { RELANE(); PHASE();
;         for (int i = vcu2; i < 512; i += G) { const int round = i >> 8, v = i & 255, bh = v >> 5, s = v & 31, x = round == 0 ? 63 - s : s; mla_unit(lds, bh, x, QM, KM, VMT, MIXRAW, SSP(layer * 8 + 7), tid, lane, wave); } }
.LBB0_1281:
	v_readlane_b32 s6, v255, 52
	v_readlane_b32 s7, v255, 53
	v_mov_b32_e32 v2, v194
	s_mov_b64 s[2:3], 0
	s_andn2_b64 vcc, exec, s[6:7]
	s_cbranch_vccnz .LBB0_1320
	v_readlane_b32 s10, v252, 7
	v_readlane_b32 s11, v252, 8
	s_add_u32 s6, s10, s2
	s_addc_u32 s7, s11, s3
	s_add_u32 s13, s6, 0x8500000
	s_addc_u32 s34, s7, 0
	v_readlane_b32 s8, v255, 46
	s_add_u32 s35, s6, 0x9d00000
	v_readlane_b32 s9, v255, 47
	s_addc_u32 s36, s7, 0
	s_lshl_b64 s[8:9], s[8:9], 3
	s_add_u32 s4, s6, s8
	s_addc_u32 s8, s7, s9
	v_and_b32_e32 v3, 31, v2
	v_bfe_u32 v4, v2, 5, 1
	v_readlane_b32 s1, v253, 48
	s_add_u32 s37, s4, 0x105f0000
	v_lshlrev_b32_e32 v15, 3, v4
	v_or_b32_e32 v165, s1, v3
	v_mul_u32_u24_e32 v7, 0x190, v3
	v_mul_u32_u24_e32 v16, 0x48, v3
	v_lshlrev_b32_e32 v164, 2, v4
	v_lshlrev_b32_e32 v3, 4, v4
	v_and_b32_e32 v4, 7, v2
	s_mov_b32 s14, 0x2aaaaaab
	s_addc_u32 s40, s8, 0
	v_mul_u32_u24_e32 v5, 0x190, v165
	s_add_i32 s4, 0, 0x1a000
	v_lshlrev_b32_e32 v18, 4, v4
	v_mul_hi_i32 v4, v2, s14
	v_add3_u32 v208, s4, v5, v3
	v_lshrrev_b32_e32 v5, 31, v4
	v_ashrrev_i32_e32 v4, 2, v4
	v_add_u32_e32 v11, v4, v5
	s_movk_i32 s15, 0xffe8
	v_mad_u64_u32 v[4:5], s[8:9], v11, s15, v[2:3]
	v_lshrrev_b32_e32 v5, 5, v11
	v_and_b32_e32 v6, 31, v11
	v_mul_i32_i24_e32 v5, 0x1900, v5
	v_mul_u32_u24_e32 v6, 0xc8, v6
	v_lshlrev_b32_e32 v8, 3, v4
	v_add3_u32 v19, v5, v6, v8
	v_add_u32_e32 v6, 0x200, v2
	v_mul_hi_i32 v5, v6, s14
	v_lshrrev_b32_e32 v8, 31, v5
	v_ashrrev_i32_e32 v5, 2, v5
	v_add_u32_e32 v5, v5, v8
	v_mad_u64_u32 v[8:9], s[8:9], v5, s15, v[6:7]
	v_lshrrev_b32_e32 v9, 5, v5
	v_and_b32_e32 v10, 31, v5
	v_mul_i32_i24_e32 v9, 0x1900, v9
	v_mul_u32_u24_e32 v10, 0xc8, v10
	v_lshlrev_b32_e32 v12, 3, v8
	v_add3_u32 v9, v9, v10, v12
	v_add_u32_e32 v10, 0x400, v2
	v_mul_hi_i32 v12, v10, s14
	v_lshrrev_b32_e32 v13, 31, v12
	v_ashrrev_i32_e32 v12, 2, v12
	v_add_u32_e32 v20, v12, v13
	v_mad_u64_u32 v[12:13], s[8:9], v20, s15, v[10:11]
	v_lshrrev_b32_e32 v13, 5, v20
	v_and_b32_e32 v14, 31, v20
	v_readlane_b32 s1, v253, 46
	v_mul_i32_i24_e32 v13, 0x1900, v13
	v_mul_u32_u24_e32 v14, 0xc8, v14
	v_lshlrev_b32_e32 v21, 3, v12
	v_add3_u32 v209, s1, v7, v3
	v_lshlrev_b32_e32 v3, 3, v2
	v_add3_u32 v13, v13, v14, v21
	v_and_b32_e32 v14, 24, v3
	v_ashrrev_i32_e32 v3, 31, v2
	s_movk_i32 s1, 0x190
	v_lshlrev_b64 v[166:167], 4, v[2:3]
	v_mul_lo_u32 v3, v11, s1
	v_add_u32_e32 v22, s4, v3
	v_ashrrev_i32_e32 v7, 31, v6
	v_mul_lo_u32 v3, v5, s1
	v_lshlrev_b32_e32 v23, 4, v4
	v_lshlrev_b64 v[168:169], 4, v[6:7]
	v_add_u32_e32 v6, s4, v3
	v_mul_lo_u32 v3, v20, s1
	v_add_u32_e32 v4, 0x600, v2
	v_lshlrev_b32_e32 v7, 4, v8
	v_add_u32_e32 v8, s4, v3
	v_mul_hi_i32 v3, v4, s14
	v_lshrrev_b32_e32 v5, 31, v3
	v_ashrrev_i32_e32 v3, 2, v3
	v_ashrrev_i32_e32 v11, 31, v10
	v_add_u32_e32 v3, v3, v5
	v_lshlrev_b64 v[170:171], 4, v[10:11]
	v_mul_lo_u32 v11, v3, s15
	v_ashrrev_i32_e32 v5, 31, v4
	v_lshlrev_b64 v[172:173], 4, v[4:5]
	v_mul_lo_u32 v3, v3, s1
	v_add_lshl_u32 v11, v11, v4, 4
	v_add_u32_e32 v4, 0x800, v2
	v_lshlrev_b32_e32 v10, 4, v12
	v_add_u32_e32 v12, s4, v3
	v_mul_hi_i32 v3, v4, s14
	v_lshrrev_b32_e32 v5, 31, v3
	v_ashrrev_i32_e32 v3, 2, v3
	v_add_u32_e32 v3, v3, v5
	v_mul_lo_u32 v20, v3, s15
	v_ashrrev_i32_e32 v5, 31, v4
	v_lshlrev_b64 v[174:175], 4, v[4:5]
	v_mul_lo_u32 v3, v3, s1
	v_add_lshl_u32 v20, v20, v4, 4
	v_add_u32_e32 v4, 0xa00, v2
	v_add_u32_e32 v24, s4, v3
	v_mul_hi_i32 v3, v4, s14
	v_lshrrev_b32_e32 v5, 31, v3
	v_ashrrev_i32_e32 v3, 2, v3
	v_add_u32_e32 v3, v3, v5
	v_ashrrev_i32_e32 v17, 3, v2
	v_bfe_u32 v21, v2, 2, 1
	v_mul_lo_u32 v25, v3, s15
	v_ashrrev_i32_e32 v5, 31, v4
	v_mul_lo_u32 v3, v3, s1
	v_and_b32_e32 v1, 63, v2
	v_lshlrev_b64 v[176:177], 4, v[4:5]
	v_add_u32_e32 v5, s4, v3
	v_lshlrev_b32_e32 v178, 4, v2
	v_mul_u32_u24_e32 v21, 0x1200, v21
	v_readlane_b32 s1, v253, 47
	v_mad_u64_u32 v[2:3], s[8:9], v17, 36, v[14:15]
	s_nop 0
	v_add3_u32 v210, s1, v16, v15
	v_add_lshl_u32 v2, v2, v21, 1
	v_readlane_b32 s1, v255, 26
	v_lshl_or_b32 v98, v17, 14, v18
	v_add_u32_e32 v214, 0, v2
	v_add_u32_e32 v2, s1, v2
	v_add_lshl_u32 v4, v25, v4, 4
	v_mov_b32_e32 v179, v99
	v_add_u32_e32 v215, 0xc800, v2
	v_readlane_b32 s1, v253, 49
	v_lshl_add_u64 v[2:3], s[6:7], 0, v[98:99]
	s_mov_b64 s[8:9], 0xb500000
	v_lshl_add_u32 v211, v19, 1, 0
	v_lshl_add_u32 v212, v9, 1, 0
	v_lshl_add_u32 v213, v13, 1, 0
	v_lshl_add_u32 v216, v1, 2, s1
	v_cmp_gt_u32_e64 s[42:43], 32, v1
	v_lshl_add_u64 v[180:181], v[2:3], 0, s[8:9]
	v_lshl_add_u64 v[182:183], s[10:11], 0, v[98:99]
	v_lshl_add_u64 v[184:185], s[10:11], 0, v[178:179]
	v_add_u32_e32 v217, v22, v23
	v_add_u32_e32 v218, v6, v7
	v_add_u32_e32 v219, v8, v10
	v_add_u32_e32 v220, v12, v11
	v_add_u32_e32 v221, v24, v20
	v_add_u32_e32 v222, v5, v4
	v_readfirstlane_b32 s1, v194
	s_cmpk_lt_u32 s1, 0x100
	s_cbranch_scc1 .Lmla_prio_skip
	s_setprio 1
.Lmla_prio_skip:
	v_readlane_b32 s41, v255, 27
	s_branch .LBB0_1285

; __device__ __forceinline__ void xcd_barrier(const XcdBarrier& b) {
;     asm volatile("s_waitcnt vmcnt(0)" ::: "memory");
;     __syncthreads();
;     if (threadIdx.x == 0) {
;         unsigned* bar = b.bar;
;         __builtin_amdgcn_s_waitcnt(0);
;         unsigned nloc = b.st[0], nx = b.st[1];
;         if (nloc == 0u) { xcd_barrier_complete(bar, b.x, nloc, nx); b.st[0] = nloc; b.st[1] = nx; }
.LBB0_1320:
	s_setprio 0
	s_waitcnt vmcnt(0)
	s_barrier
	s_mov_b64 s[2:3], exec
	v_readlane_b32 s6, v252, 10
	v_readlane_b32 s7, v252, 11
	s_and_b64 s[6:7], s[2:3], s[6:7]
	s_mov_b64 exec, s[6:7]
	s_cbranch_execz .LBB0_1372
	v_readlane_b32 s1, v255, 21
	s_waitcnt vmcnt(0) expcnt(0) lgkmcnt(0)
	s_nop 0
	v_mov_b32_e32 v1, s1
	ds_read_b32 v3, v1
	v_readlane_b32 s1, v255, 22
	s_waitcnt lgkmcnt(0)
	v_cmp_ne_u32_e32 vcc, 0, v3
	v_mov_b32_e32 v1, s1
	ds_read_b32 v2, v1
	s_cbranch_vccnz .LBB0_1336
	s_mov_b32 s4, 1
	s_branch .LBB0_1324
